# stream GEMM loops of proj and one more GEMM: stage d of the first K tile moved from S2.L(0) to the start of S1.L(1) (DMA pieces per load interval 2/6/2/6 -> 2/4/4/6), closing wait vmcnt(6); on v25
# speedup vs baseline: 1.0067x; 1.0067x over previous
; template <class EPI>
; DI void gemm_stream(const u16* __restrict__ A, const u16* __restrict__ Bt, const int K, const int nM, const int nN,
;                     const int bid, const int nb, const int tid, EPI epi) {
;     ...
;     for (int t = 0; t < nt; t += 2) {
;       const bool inside = (t + 2 < nt);
;       const int brs = inside ? brow : brow2, bcs = inside ? bcol : bcol2, t2 = inside ? t + 2 : 0;
.LBB0_32:
	s_add_i32 s11, s10, 2
	ds_read_b128 v[132:135], v159
	ds_read_b128 v[136:139], v160
	ds_read_b128 v[180:183], v161
	ds_read_b128 v[184:187], v162
	s_cmpk_lt_u32 s10, 0x56
	s_cselect_b32 s12, s8, s5
	s_cselect_b32 s13, s7, s6
	s_cselect_b32 s14, s9, 0
	s_mulk_i32 s13, 0x1600
	s_mulk_i32 s12, 0x1600
	s_or_b32 s15, s14, 64
	s_add_i32 s17, s12, s14
	s_add_i32 s18, s13, 0xb0000
	s_add_i32 s16, s13, s14
	s_add_i32 s13, s15, s13
	s_add_i32 s12, s15, s12
	s_lshl_b32 s17, s17, 1
	s_add_i32 s14, s18, s14
	s_add_i32 s18, s18, s15
	s_addk_i32 s9, 0x80
	s_lshl_b32 s16, s16, 1
	s_lshl_b32 s19, s13, 1
	s_lshl_b32 s13, s12, 1
	s_lshl_b32 s14, s14, 1
	s_add_i32 s15, s17, 0x160000
	s_lshl_b32 s12, s18, 1
	s_cmpk_gt_u32 s10, 0x55
	v_readfirstlane_b32 s10, v163
	v_add_u32_e32 v131, 0xfff50000, v130
	s_mov_b32 m0, s10
	v_readfirstlane_b32 s10, v165
	ds_read_b128 v[188:191], v157
	ds_read_b128 v[192:195], v157 offset:1024
	ds_read_b128 v[196:199], v157 offset:2048
	ds_read_b128 v[200:203], v157 offset:3072
	ds_read_b128 v[204:207], v157 offset:4096
	ds_read_b128 v[208:211], v157 offset:5120
	ds_read_b128 v[212:215], v157 offset:6144
	ds_read_b128 v[216:219], v157 offset:7168
	global_load_lds_dwordx4 v131, s[76:77]
	s_mov_b32 m0, s10
	s_nop 0
	global_load_lds_dwordx4 v130, s[76:77]
	s_waitcnt lgkmcnt(8)
	ds_read_b128 v[220:223], v166
	ds_read_b128 v[242:245], v167
	ds_read_b128 v[246:249], v168
	ds_read_b128 v[250:253], v169
	s_waitcnt vmcnt(8)
	s_waitcnt lgkmcnt(0)
	s_barrier
	v_mfma_f32_16x16x32_bf16 v[126:129], v[132:135], v[188:191], v[126:129]
	v_mfma_f32_16x16x32_bf16 v[122:125], v[180:183], v[188:191], v[122:125]
	v_mfma_f32_16x16x32_bf16 v[118:121], v[132:135], v[196:199], v[118:121]
	v_mfma_f32_16x16x32_bf16 v[114:117], v[180:183], v[196:199], v[114:117]
	v_mfma_f32_16x16x32_bf16 v[110:113], v[132:135], v[204:207], v[110:113]
	v_mfma_f32_16x16x32_bf16 v[106:109], v[180:183], v[204:207], v[106:109]
	v_mfma_f32_16x16x32_bf16 v[102:105], v[132:135], v[212:215], v[102:105]
	v_mfma_f32_16x16x32_bf16 v[98:101], v[180:183], v[212:215], v[98:101]
	v_mfma_f32_16x16x32_bf16 v[126:129], v[136:139], v[192:195], v[126:129]
	v_mfma_f32_16x16x32_bf16 v[122:125], v[184:187], v[192:195], v[122:125]
	v_mfma_f32_16x16x32_bf16 v[118:121], v[136:139], v[200:203], v[118:121]
	v_mfma_f32_16x16x32_bf16 v[114:117], v[184:187], v[200:203], v[114:117]
	v_mfma_f32_16x16x32_bf16 v[110:113], v[136:139], v[208:211], v[110:113]
	v_mfma_f32_16x16x32_bf16 v[106:109], v[184:187], v[208:211], v[106:109]
	v_mfma_f32_16x16x32_bf16 v[102:105], v[136:139], v[216:219], v[102:105]
	v_mfma_f32_16x16x32_bf16 v[98:101], v[184:187], v[216:219], v[98:101]
	v_mfma_f32_16x16x32_bf16 v[94:97], v[220:223], v[188:191], v[94:97]
	v_mfma_f32_16x16x32_bf16 v[90:93], v[246:249], v[188:191], v[90:93]
	v_mfma_f32_16x16x32_bf16 v[86:89], v[220:223], v[196:199], v[86:89]
	v_mfma_f32_16x16x32_bf16 v[82:85], v[246:249], v[196:199], v[82:85]
	v_mfma_f32_16x16x32_bf16 v[78:81], v[220:223], v[204:207], v[78:81]
	v_mfma_f32_16x16x32_bf16 v[74:77], v[246:249], v[204:207], v[74:77]
	v_mfma_f32_16x16x32_bf16 v[70:73], v[220:223], v[212:215], v[70:73]
	v_mfma_f32_16x16x32_bf16 v[66:69], v[246:249], v[212:215], v[66:69]
	v_mfma_f32_16x16x32_bf16 v[94:97], v[242:245], v[192:195], v[94:97]
	v_mfma_f32_16x16x32_bf16 v[90:93], v[250:253], v[192:195], v[90:93]
	v_mfma_f32_16x16x32_bf16 v[86:89], v[242:245], v[200:203], v[86:89]
	v_mfma_f32_16x16x32_bf16 v[82:85], v[250:253], v[200:203], v[82:85]
	v_mfma_f32_16x16x32_bf16 v[78:81], v[242:245], v[208:211], v[78:81]
	v_mfma_f32_16x16x32_bf16 v[74:77], v[250:253], v[208:211], v[74:77]
	v_mfma_f32_16x16x32_bf16 v[70:73], v[242:245], v[216:219], v[70:73]
	v_mfma_f32_16x16x32_bf16 v[66:69], v[250:253], v[216:219], v[66:69]
	s_barrier
	v_readfirstlane_b32 s10, v144
	v_add_u32_e32 v131, s16, v142
	s_mov_b32 m0, s10
	v_readfirstlane_b32 s10, v145
	global_load_lds_dwordx4 v131, s[78:79]
	v_add_u32_e32 v131, s16, v143
	s_mov_b32 m0, s10
	s_nop 0
	global_load_lds_dwordx4 v131, s[78:79]
	v_readfirstlane_b32 s10, v0
	v_add_u32_e32 v131, s17, v142
	s_mov_b32 m0, s10
	v_readfirstlane_b32 s10, v146
	ds_read_b128 v[188:191], v157 offset:16384
	ds_read_b128 v[192:195], v157 offset:17408
	ds_read_b128 v[196:199], v157 offset:18432
	ds_read_b128 v[200:203], v157 offset:19456
	ds_read_b128 v[204:207], v157 offset:20480
	ds_read_b128 v[208:211], v157 offset:21504
	ds_read_b128 v[212:215], v157 offset:22528
	ds_read_b128 v[216:219], v157 offset:23552
	global_load_lds_dwordx4 v131, s[76:77]
	v_add_u32_e32 v131, s17, v143
	s_mov_b32 m0, s10
	s_nop 0
	global_load_lds_dwordx4 v131, s[76:77]
	s_waitcnt vmcnt(6)
	s_waitcnt lgkmcnt(0)
	s_barrier
	v_mfma_f32_16x16x32_bf16 v[62:65], v[132:135], v[188:191], v[62:65]
	v_mfma_f32_16x16x32_bf16 v[58:61], v[180:183], v[188:191], v[58:61]
	v_mfma_f32_16x16x32_bf16 v[54:57], v[132:135], v[196:199], v[54:57]
	v_mfma_f32_16x16x32_bf16 v[50:53], v[180:183], v[196:199], v[50:53]
	v_mfma_f32_16x16x32_bf16 v[46:49], v[132:135], v[204:207], v[46:49]
	v_mfma_f32_16x16x32_bf16 v[42:45], v[180:183], v[204:207], v[42:45]
	v_mfma_f32_16x16x32_bf16 v[38:41], v[132:135], v[212:215], v[38:41]
	v_mfma_f32_16x16x32_bf16 v[34:37], v[180:183], v[212:215], v[34:37]
	v_mfma_f32_16x16x32_bf16 v[62:65], v[136:139], v[192:195], v[62:65]
	v_mfma_f32_16x16x32_bf16 v[58:61], v[184:187], v[192:195], v[58:61]
	v_mfma_f32_16x16x32_bf16 v[54:57], v[136:139], v[200:203], v[54:57]
	v_mfma_f32_16x16x32_bf16 v[50:53], v[184:187], v[200:203], v[50:53]
	v_mfma_f32_16x16x32_bf16 v[46:49], v[136:139], v[208:211], v[46:49]
	v_mfma_f32_16x16x32_bf16 v[42:45], v[184:187], v[208:211], v[42:45]
	v_mfma_f32_16x16x32_bf16 v[38:41], v[136:139], v[216:219], v[38:41]
	v_mfma_f32_16x16x32_bf16 v[34:37], v[184:187], v[216:219], v[34:37]
	v_mfma_f32_16x16x32_bf16 v[30:33], v[220:223], v[188:191], v[30:33]
	v_mfma_f32_16x16x32_bf16 v[26:29], v[246:249], v[188:191], v[26:29]
	v_mfma_f32_16x16x32_bf16 v[22:25], v[220:223], v[196:199], v[22:25]
	v_mfma_f32_16x16x32_bf16 v[18:21], v[246:249], v[196:199], v[18:21]
	v_mfma_f32_16x16x32_bf16 v[14:17], v[220:223], v[204:207], v[14:17]
	v_mfma_f32_16x16x32_bf16 v[10:13], v[246:249], v[204:207], v[10:13]
	v_mfma_f32_16x16x32_bf16 v[6:9], v[220:223], v[212:215], v[6:9]
	v_mfma_f32_16x16x32_bf16 v[2:5], v[246:249], v[212:215], v[2:5]
	v_mfma_f32_16x16x32_bf16 v[30:33], v[242:245], v[192:195], v[30:33]
	v_mfma_f32_16x16x32_bf16 v[26:29], v[250:253], v[192:195], v[26:29]
	v_mfma_f32_16x16x32_bf16 v[22:25], v[242:245], v[200:203], v[22:25]
	v_mfma_f32_16x16x32_bf16 v[18:21], v[250:253], v[200:203], v[18:21]
	v_mfma_f32_16x16x32_bf16 v[14:17], v[242:245], v[208:211], v[14:17]
	v_mfma_f32_16x16x32_bf16 v[10:13], v[250:253], v[208:211], v[10:13]
	v_mfma_f32_16x16x32_bf16 v[6:9], v[242:245], v[216:219], v[6:9]
	v_mfma_f32_16x16x32_bf16 v[2:5], v[250:253], v[216:219], v[2:5]
	s_barrier
	ds_read_b128 v[132:135], v170
	ds_read_b128 v[136:139], v171
	ds_read_b128 v[180:183], v172
	ds_read_b128 v[184:187], v173
	v_readfirstlane_b32 s10, v147
	v_add_u32_e32 v131, s14, v142
	s_mov_b32 m0, s10
	v_readfirstlane_b32 s10, v148
	global_load_lds_dwordx4 v131, s[78:79]
	v_add_u32_e32 v131, s14, v143
	s_mov_b32 m0, s10
	s_nop 0
	global_load_lds_dwordx4 v131, s[78:79]
	v_readfirstlane_b32 s10, v149
	v_add_u32_e32 v131, s15, v142
	s_mov_b32 m0, s10
	v_readfirstlane_b32 s10, v150
	ds_read_b128 v[188:191], v157 offset:32768
	ds_read_b128 v[192:195], v157 offset:33792
	ds_read_b128 v[196:199], v157 offset:34816
	ds_read_b128 v[200:203], v157 offset:35840
	ds_read_b128 v[204:207], v157 offset:36864
	ds_read_b128 v[208:211], v157 offset:37888
	ds_read_b128 v[212:215], v157 offset:38912
	ds_read_b128 v[216:219], v157 offset:39936
	global_load_lds_dwordx4 v131, s[76:77]
	v_add_u32_e32 v131, s15, v143
	s_mov_b32 m0, s10
	s_nop 0
	global_load_lds_dwordx4 v131, s[76:77]
	s_waitcnt lgkmcnt(8)
	ds_read_b128 v[220:223], v174
	ds_read_b128 v[242:245], v175
	ds_read_b128 v[246:249], v176
	ds_read_b128 v[250:253], v177
	s_waitcnt vmcnt(8)
	s_waitcnt lgkmcnt(0)
	s_barrier
	v_mfma_f32_16x16x32_bf16 v[126:129], v[132:135], v[188:191], v[126:129]
	v_mfma_f32_16x16x32_bf16 v[122:125], v[180:183], v[188:191], v[122:125]
	v_mfma_f32_16x16x32_bf16 v[118:121], v[132:135], v[196:199], v[118:121]
	v_mfma_f32_16x16x32_bf16 v[114:117], v[180:183], v[196:199], v[114:117]
	v_mfma_f32_16x16x32_bf16 v[110:113], v[132:135], v[204:207], v[110:113]
	v_mfma_f32_16x16x32_bf16 v[106:109], v[180:183], v[204:207], v[106:109]
	v_mfma_f32_16x16x32_bf16 v[102:105], v[132:135], v[212:215], v[102:105]
	v_mfma_f32_16x16x32_bf16 v[98:101], v[180:183], v[212:215], v[98:101]
	v_mfma_f32_16x16x32_bf16 v[126:129], v[136:139], v[192:195], v[126:129]
	v_mfma_f32_16x16x32_bf16 v[122:125], v[184:187], v[192:195], v[122:125]
	v_mfma_f32_16x16x32_bf16 v[118:121], v[136:139], v[200:203], v[118:121]
	v_mfma_f32_16x16x32_bf16 v[114:117], v[184:187], v[200:203], v[114:117]
	v_mfma_f32_16x16x32_bf16 v[110:113], v[136:139], v[208:211], v[110:113]
	v_mfma_f32_16x16x32_bf16 v[106:109], v[184:187], v[208:211], v[106:109]
	v_mfma_f32_16x16x32_bf16 v[102:105], v[136:139], v[216:219], v[102:105]
	v_mfma_f32_16x16x32_bf16 v[98:101], v[184:187], v[216:219], v[98:101]
	v_mfma_f32_16x16x32_bf16 v[94:97], v[220:223], v[188:191], v[94:97]
	v_mfma_f32_16x16x32_bf16 v[90:93], v[246:249], v[188:191], v[90:93]
	v_mfma_f32_16x16x32_bf16 v[86:89], v[220:223], v[196:199], v[86:89]
	v_mfma_f32_16x16x32_bf16 v[82:85], v[246:249], v[196:199], v[82:85]
	v_mfma_f32_16x16x32_bf16 v[78:81], v[220:223], v[204:207], v[78:81]
	v_mfma_f32_16x16x32_bf16 v[74:77], v[246:249], v[204:207], v[74:77]
	v_mfma_f32_16x16x32_bf16 v[70:73], v[220:223], v[212:215], v[70:73]
	v_mfma_f32_16x16x32_bf16 v[66:69], v[246:249], v[212:215], v[66:69]
	v_mfma_f32_16x16x32_bf16 v[94:97], v[242:245], v[192:195], v[94:97]
	v_mfma_f32_16x16x32_bf16 v[90:93], v[250:253], v[192:195], v[90:93]
	v_mfma_f32_16x16x32_bf16 v[86:89], v[242:245], v[200:203], v[86:89]
	v_mfma_f32_16x16x32_bf16 v[82:85], v[250:253], v[200:203], v[82:85]
	v_mfma_f32_16x16x32_bf16 v[78:81], v[242:245], v[208:211], v[78:81]
	v_mfma_f32_16x16x32_bf16 v[74:77], v[250:253], v[208:211], v[74:77]
	v_mfma_f32_16x16x32_bf16 v[70:73], v[242:245], v[216:219], v[70:73]
	v_mfma_f32_16x16x32_bf16 v[66:69], v[250:253], v[216:219], v[66:69]
	s_barrier
; DI void gemm_resid(const u16* A, const u16* Bt, int K, const float* xin, float* xout, int bid, int nb, int tid) {
;     ...
;     for (int ai = 0; ai < 2; ++ai)
; #pragma unroll
;       for (int bj = 0; bj < 2; ++bj) {
;         float4 xi[4][2];
; #pragma unroll
;         for (int m = 0; m < 4; ++m)
; #pragma unroll
;           for (int n = 0; n < 2; ++n) xi[m][n] = *reinterpret_cast<const float4*>(xin + (size_t)ACC_ROW * 2048 + ACC_COL);
	v_readfirstlane_b32 s10, v151
	v_add_u32_e32 v131, s19, v142
	s_mov_b32 m0, s10
	v_readfirstlane_b32 s10, v152
	global_load_lds_dwordx4 v131, s[78:79]
	v_add_u32_e32 v131, s19, v143
	s_mov_b32 m0, s10
	s_nop 0
	global_load_lds_dwordx4 v131, s[78:79]
	v_readfirstlane_b32 s10, v153
	v_add_u32_e32 v131, s13, v142
	s_mov_b32 m0, s10
	v_readfirstlane_b32 s10, v154
	ds_read_b128 v[188:191], v157 offset:49152
	ds_read_b128 v[192:195], v157 offset:50176
	ds_read_b128 v[196:199], v157 offset:51200
	ds_read_b128 v[200:203], v157 offset:52224
	ds_read_b128 v[204:207], v157 offset:53248
	ds_read_b128 v[208:211], v157 offset:54272
	ds_read_b128 v[212:215], v157 offset:55296
	ds_read_b128 v[216:219], v157 offset:56320
	global_load_lds_dwordx4 v131, s[76:77]
	v_add_u32_e32 v131, s13, v143
	s_mov_b32 m0, s10
	s_nop 0
	global_load_lds_dwordx4 v131, s[76:77]
	v_readfirstlane_b32 s10, v155
	v_add_u32_e32 v131, s12, v142
	s_mov_b32 m0, s10
	v_readfirstlane_b32 s10, v156
	global_load_lds_dwordx4 v131, s[78:79]
	v_add_u32_e32 v131, s12, v143
	s_mov_b32 m0, s10
	s_nop 0
	global_load_lds_dwordx4 v131, s[78:79]
	s_waitcnt vmcnt(8)
	s_waitcnt lgkmcnt(0)
	s_barrier
	v_mfma_f32_16x16x32_bf16 v[62:65], v[132:135], v[188:191], v[62:65]
	v_mfma_f32_16x16x32_bf16 v[58:61], v[180:183], v[188:191], v[58:61]
	v_mfma_f32_16x16x32_bf16 v[54:57], v[132:135], v[196:199], v[54:57]
	v_mfma_f32_16x16x32_bf16 v[50:53], v[180:183], v[196:199], v[50:53]
	v_mfma_f32_16x16x32_bf16 v[46:49], v[132:135], v[204:207], v[46:49]
	v_mfma_f32_16x16x32_bf16 v[42:45], v[180:183], v[204:207], v[42:45]
	v_mfma_f32_16x16x32_bf16 v[38:41], v[132:135], v[212:215], v[38:41]
	v_mfma_f32_16x16x32_bf16 v[34:37], v[180:183], v[212:215], v[34:37]
	v_mfma_f32_16x16x32_bf16 v[62:65], v[136:139], v[192:195], v[62:65]
	v_mfma_f32_16x16x32_bf16 v[58:61], v[184:187], v[192:195], v[58:61]
	v_mfma_f32_16x16x32_bf16 v[54:57], v[136:139], v[200:203], v[54:57]
	v_mfma_f32_16x16x32_bf16 v[50:53], v[184:187], v[200:203], v[50:53]
	v_mfma_f32_16x16x32_bf16 v[46:49], v[136:139], v[208:211], v[46:49]
	v_mfma_f32_16x16x32_bf16 v[42:45], v[184:187], v[208:211], v[42:45]
	v_mfma_f32_16x16x32_bf16 v[38:41], v[136:139], v[216:219], v[38:41]
	v_mfma_f32_16x16x32_bf16 v[34:37], v[184:187], v[216:219], v[34:37]
	v_mfma_f32_16x16x32_bf16 v[30:33], v[220:223], v[188:191], v[30:33]
	v_mfma_f32_16x16x32_bf16 v[26:29], v[246:249], v[188:191], v[26:29]
	v_mfma_f32_16x16x32_bf16 v[22:25], v[220:223], v[196:199], v[22:25]
	v_mfma_f32_16x16x32_bf16 v[18:21], v[246:249], v[196:199], v[18:21]
	v_mfma_f32_16x16x32_bf16 v[14:17], v[220:223], v[204:207], v[14:17]
	v_mfma_f32_16x16x32_bf16 v[10:13], v[246:249], v[204:207], v[10:13]
	v_mfma_f32_16x16x32_bf16 v[6:9], v[220:223], v[212:215], v[6:9]
	v_mfma_f32_16x16x32_bf16 v[2:5], v[246:249], v[212:215], v[2:5]
	v_mfma_f32_16x16x32_bf16 v[30:33], v[242:245], v[192:195], v[30:33]
	v_mfma_f32_16x16x32_bf16 v[26:29], v[250:253], v[192:195], v[26:29]
	v_mfma_f32_16x16x32_bf16 v[22:25], v[242:245], v[200:203], v[22:25]
	v_mfma_f32_16x16x32_bf16 v[18:21], v[250:253], v[200:203], v[18:21]
	v_mfma_f32_16x16x32_bf16 v[14:17], v[242:245], v[208:211], v[14:17]
	v_mfma_f32_16x16x32_bf16 v[10:13], v[250:253], v[208:211], v[10:13]
	v_mfma_f32_16x16x32_bf16 v[6:9], v[242:245], v[216:219], v[6:9]
	v_mfma_f32_16x16x32_bf16 v[2:5], v[250:253], v[216:219], v[2:5]
	v_add_u32_e32 v130, 0x100, v130
	s_mov_b32 s10, s11
	s_barrier
	s_cbranch_scc0 .LBB0_32
	v_mov_b32_e32 v131, v239
	s_nop 0
	v_ashrrev_i32_e32 v130, 2, v131
	v_and_b32_e32 v130, 0xffffffc0, v130
	v_and_or_b32 v132, v131, 15, s8
	v_add_u32_e32 v130, v132, v130
	v_lshrrev_b32_e32 v132, 1, v131
	v_lshrrev_b32_e32 v131, 2, v131
	v_and_b32_e32 v132, 0x60, v132
	v_and_b32_e32 v131, 12, v131
	v_or3_b32 v132, v132, v131, s7
	v_ashrrev_i32_e32 v131, 31, v130
	v_ashrrev_i32_e32 v133, 31, v132
	v_lshlrev_b64 v[134:135], 13, v[130:131]
	v_lshl_add_u64 v[134:135], s[72:73], 0, v[134:135]
	v_lshlrev_b64 v[132:133], 2, v[132:133]
	v_lshl_add_u64 v[140:141], v[134:135], 0, v[132:133]
	v_or_b32_e32 v134, 16, v130
	v_ashrrev_i32_e32 v135, 31, v134
	v_lshlrev_b64 v[134:135], 13, v[134:135]
	v_lshl_add_u64 v[134:135], s[72:73], 0, v[134:135]
	v_lshl_add_u64 v[138:139], v[134:135], 0, v[132:133]
	v_or_b32_e32 v134, 32, v130
	v_ashrrev_i32_e32 v135, 31, v134
	v_lshlrev_b64 v[134:135], 13, v[134:135]
	v_lshl_add_u64 v[134:135], s[72:73], 0, v[134:135]
	v_lshl_add_u64 v[136:137], v[134:135], 0, v[132:133]
	v_or_b32_e32 v134, 48, v130
	v_ashrrev_i32_e32 v135, 31, v134
	v_lshlrev_b64 v[134:135], 13, v[134:135]
	v_lshl_add_u64 v[134:135], s[72:73], 0, v[134:135]
	v_lshl_add_u64 v[134:135], v[134:135], 0, v[132:133]
	global_load_dwordx4 v[180:183], v[140:141], off
	global_load_dwordx4 v[184:187], v[140:141], off offset:64
	global_load_dwordx4 v[188:191], v[138:139], off
	global_load_dwordx4 v[192:195], v[138:139], off offset:64
	global_load_dwordx4 v[196:199], v[136:137], off
	global_load_dwordx4 v[200:203], v[136:137], off offset:64
	global_load_dwordx4 v[204:207], v[134:135], off
	global_load_dwordx4 v[208:211], v[134:135], off offset:64
	s_waitcnt vmcnt(0)
; #define EPI_SCHED __builtin_amdgcn_sched_barrier(0)
; template <class EPI>
; DI void gemm_stream(const u16* __restrict__ A, const u16* __restrict__ Bt, const int K, const int nM, const int nN,
;                     const int bid, const int nb, const int tid, EPI epi) {
;     ...
;     epi(acc, brow, bcol, pn);
; #pragma unroll
;     for (int ai = 0; ai < 2; ++ai)
; #pragma unroll
;       for (int bj = 0; bj < 2; ++bj)
; #pragma unroll
;         for (int m = 0; m < 4; ++m)
; #pragma unroll
;           for (int n = 0; n < 2; ++n) acc[ai][bj][m][n] = (f32x4){0.f, 0.f, 0.f, 0.f};
;     brow = brow2; bcol = bcol2; pm = pm2; pn = pn2;
; DI void gemm_resid(const u16* A, const u16* Bt, int K, const float* xin, float* xout, int bid, int nb, int tid) {
;     ...
;           for (int n = 0; n < 2; ++n) xi[m][n] = *reinterpret_cast<const float4*>(xin + (size_t)ACC_ROW * 2048 + ACC_COL);
; #pragma unroll
;         for (int m = 0; m < 4; ++m)
; #pragma unroll
;           for (int n = 0; n < 2; ++n) {
;             const f32x4 v = acc[ai][bj][m][n];
;             float4 r; r.x = xi[m][n].x + v[0]; r.y = xi[m][n].y + v[1]; r.z = xi[m][n].z + v[2]; r.w = xi[m][n].w + v[3];
;             *reinterpret_cast<float4*>(xout + (size_t)ACC_ROW * 2048 + ACC_COL) = r;
;           }
;         EPI_SCHED;
	v_pk_add_f32 v[126:127], v[126:127], v[180:181]
	v_pk_add_f32 v[128:129], v[128:129], v[182:183]
	global_store_dwordx4 v[140:141], v[126:129], off
	v_pk_add_f32 v[122:123], v[122:123], v[184:185]
	v_pk_add_f32 v[124:125], v[124:125], v[186:187]
	global_store_dwordx4 v[140:141], v[122:125], off offset:64
	v_pk_add_f32 v[118:119], v[118:119], v[188:189]
	v_pk_add_f32 v[120:121], v[120:121], v[190:191]
	global_store_dwordx4 v[138:139], v[118:121], off
	v_pk_add_f32 v[114:115], v[114:115], v[192:193]
	v_pk_add_f32 v[116:117], v[116:117], v[194:195]
	global_store_dwordx4 v[138:139], v[114:117], off offset:64
	v_pk_add_f32 v[110:111], v[110:111], v[196:197]
	v_pk_add_f32 v[112:113], v[112:113], v[198:199]
	global_store_dwordx4 v[136:137], v[110:113], off
	v_pk_add_f32 v[106:107], v[106:107], v[200:201]
	v_pk_add_f32 v[108:109], v[108:109], v[202:203]
	global_store_dwordx4 v[136:137], v[106:109], off offset:64
	v_pk_add_f32 v[102:103], v[102:103], v[204:205]
	v_pk_add_f32 v[104:105], v[104:105], v[206:207]
	global_store_dwordx4 v[134:135], v[102:105], off
	v_pk_add_f32 v[98:99], v[98:99], v[208:209]
	v_pk_add_f32 v[100:101], v[100:101], v[210:211]
	global_store_dwordx4 v[134:135], v[98:101], off offset:64
	global_load_dwordx4 v[180:183], v[140:141], off offset:512
	global_load_dwordx4 v[184:187], v[140:141], off offset:576
	global_load_dwordx4 v[188:191], v[138:139], off offset:512
	global_load_dwordx4 v[192:195], v[138:139], off offset:576
	global_load_dwordx4 v[196:199], v[136:137], off offset:512
	global_load_dwordx4 v[200:203], v[136:137], off offset:576
	global_load_dwordx4 v[204:207], v[134:135], off offset:512
	global_load_dwordx4 v[208:211], v[134:135], off offset:576
	s_waitcnt vmcnt(0)
	v_pk_add_f32 v[94:95], v[94:95], v[180:181]
	v_pk_add_f32 v[96:97], v[96:97], v[182:183]
	global_store_dwordx4 v[140:141], v[94:97], off offset:512
	v_pk_add_f32 v[90:91], v[90:91], v[184:185]
	v_pk_add_f32 v[92:93], v[92:93], v[186:187]
	global_store_dwordx4 v[140:141], v[90:93], off offset:576
	v_pk_add_f32 v[86:87], v[86:87], v[188:189]
	v_pk_add_f32 v[88:89], v[88:89], v[190:191]
	global_store_dwordx4 v[138:139], v[86:89], off offset:512
	v_pk_add_f32 v[82:83], v[82:83], v[192:193]
	v_pk_add_f32 v[84:85], v[84:85], v[194:195]
	global_store_dwordx4 v[138:139], v[82:85], off offset:576
	v_pk_add_f32 v[78:79], v[78:79], v[196:197]
	v_pk_add_f32 v[80:81], v[80:81], v[198:199]
	global_store_dwordx4 v[136:137], v[78:81], off offset:512
	v_pk_add_f32 v[74:75], v[74:75], v[200:201]
	v_pk_add_f32 v[76:77], v[76:77], v[202:203]
	global_store_dwordx4 v[136:137], v[74:77], off offset:576
	v_pk_add_f32 v[70:71], v[70:71], v[204:205]
	v_pk_add_f32 v[72:73], v[72:73], v[206:207]
	global_store_dwordx4 v[134:135], v[70:73], off offset:512
	v_pk_add_f32 v[66:67], v[66:67], v[208:209]
	v_pk_add_f32 v[68:69], v[68:69], v[210:211]
	global_store_dwordx4 v[134:135], v[66:69], off offset:576
	s_nop 1
	v_add_u32_e32 v66, 0x80, v130
	v_ashrrev_i32_e32 v67, 31, v66
	v_lshlrev_b64 v[66:67], 13, v[66:67]
	v_lshl_add_u64 v[66:67], s[72:73], 0, v[66:67]
	v_lshl_add_u64 v[72:73], v[66:67], 0, v[132:133]
	v_add_u32_e32 v66, 0x90, v130
	v_ashrrev_i32_e32 v67, 31, v66
	v_lshlrev_b64 v[66:67], 13, v[66:67]
	v_lshl_add_u64 v[66:67], s[72:73], 0, v[66:67]
	v_lshl_add_u64 v[70:71], v[66:67], 0, v[132:133]
	v_add_u32_e32 v66, 0xa0, v130
	v_ashrrev_i32_e32 v67, 31, v66
	v_lshlrev_b64 v[66:67], 13, v[66:67]
	v_lshl_add_u64 v[66:67], s[72:73], 0, v[66:67]
	v_lshl_add_u64 v[68:69], v[66:67], 0, v[132:133]
	v_add_u32_e32 v66, 0xb0, v130
	v_ashrrev_i32_e32 v67, 31, v66
	v_lshlrev_b64 v[66:67], 13, v[66:67]
	v_lshl_add_u64 v[66:67], s[72:73], 0, v[66:67]
	v_lshl_add_u64 v[66:67], v[66:67], 0, v[132:133]
	global_load_dwordx4 v[180:183], v[72:73], off
	global_load_dwordx4 v[184:187], v[72:73], off offset:64
	global_load_dwordx4 v[188:191], v[70:71], off
	global_load_dwordx4 v[192:195], v[70:71], off offset:64
	global_load_dwordx4 v[196:199], v[68:69], off
	global_load_dwordx4 v[200:203], v[68:69], off offset:64
	global_load_dwordx4 v[204:207], v[66:67], off
	global_load_dwordx4 v[208:211], v[66:67], off offset:64
	s_waitcnt vmcnt(0)
	v_pk_add_f32 v[62:63], v[62:63], v[180:181]
	v_pk_add_f32 v[64:65], v[64:65], v[182:183]
	global_store_dwordx4 v[72:73], v[62:65], off
	v_pk_add_f32 v[58:59], v[58:59], v[184:185]
	v_pk_add_f32 v[60:61], v[60:61], v[186:187]
	global_store_dwordx4 v[72:73], v[58:61], off offset:64
	v_pk_add_f32 v[54:55], v[54:55], v[188:189]
	v_pk_add_f32 v[56:57], v[56:57], v[190:191]
	global_store_dwordx4 v[70:71], v[54:57], off
	v_pk_add_f32 v[50:51], v[50:51], v[192:193]
	v_pk_add_f32 v[52:53], v[52:53], v[194:195]
	global_store_dwordx4 v[70:71], v[50:53], off offset:64
	v_pk_add_f32 v[46:47], v[46:47], v[196:197]
	v_pk_add_f32 v[48:49], v[48:49], v[198:199]
	global_store_dwordx4 v[68:69], v[46:49], off
	v_pk_add_f32 v[42:43], v[42:43], v[200:201]
	v_pk_add_f32 v[44:45], v[44:45], v[202:203]
	global_store_dwordx4 v[68:69], v[42:45], off offset:64
	v_pk_add_f32 v[38:39], v[38:39], v[204:205]
	v_pk_add_f32 v[40:41], v[40:41], v[206:207]
	global_store_dwordx4 v[66:67], v[38:41], off
	v_pk_add_f32 v[34:35], v[34:35], v[208:209]
	v_pk_add_f32 v[36:37], v[36:37], v[210:211]
	global_store_dwordx4 v[66:67], v[34:37], off offset:64
	global_load_dwordx4 v[180:183], v[72:73], off offset:512
	global_load_dwordx4 v[184:187], v[72:73], off offset:576
	global_load_dwordx4 v[188:191], v[70:71], off offset:512
	global_load_dwordx4 v[192:195], v[70:71], off offset:576
	global_load_dwordx4 v[196:199], v[68:69], off offset:512
	global_load_dwordx4 v[200:203], v[68:69], off offset:576
	global_load_dwordx4 v[204:207], v[66:67], off offset:512
	global_load_dwordx4 v[208:211], v[66:67], off offset:576
	s_waitcnt vmcnt(0)
	v_pk_add_f32 v[30:31], v[30:31], v[180:181]
	v_pk_add_f32 v[32:33], v[32:33], v[182:183]
	global_store_dwordx4 v[72:73], v[30:33], off offset:512
	v_pk_add_f32 v[26:27], v[26:27], v[184:185]
	v_pk_add_f32 v[28:29], v[28:29], v[186:187]
	global_store_dwordx4 v[72:73], v[26:29], off offset:576
	v_pk_add_f32 v[22:23], v[22:23], v[188:189]
	v_pk_add_f32 v[24:25], v[24:25], v[190:191]
	global_store_dwordx4 v[70:71], v[22:25], off offset:512
	v_pk_add_f32 v[18:19], v[18:19], v[192:193]
	v_pk_add_f32 v[20:21], v[20:21], v[194:195]
	global_store_dwordx4 v[70:71], v[18:21], off offset:576
	v_pk_add_f32 v[14:15], v[14:15], v[196:197]
	v_pk_add_f32 v[16:17], v[16:17], v[198:199]
	global_store_dwordx4 v[68:69], v[14:17], off offset:512
	v_pk_add_f32 v[10:11], v[10:11], v[200:201]
	v_pk_add_f32 v[12:13], v[12:13], v[202:203]
	global_store_dwordx4 v[68:69], v[10:13], off offset:576
	v_pk_add_f32 v[6:7], v[6:7], v[204:205]
	v_pk_add_f32 v[8:9], v[8:9], v[206:207]
	global_store_dwordx4 v[66:67], v[6:9], off offset:512
	v_pk_add_f32 v[2:3], v[2:3], v[208:209]
	v_pk_add_f32 v[4:5], v[4:5], v[210:211]
	global_store_dwordx4 v[66:67], v[2:5], off offset:576
	s_and_b64 vcc, exec, s[0:1]
	s_mov_b32 s8, s5
	s_mov_b32 s7, s6
	s_cbranch_vccz .LBB0_29
; #define WAIT_V(n) asm volatile("s_waitcnt vmcnt(" #n ")" ::: "memory")
; #define BAR __builtin_amdgcn_s_barrier()
; template <class EPI>
; DI void gemm_stream(const u16* __restrict__ A, const u16* __restrict__ Bt, const int K, const int nM, const int nN,
;                     const int bid, const int nb, const int tid, EPI epi) {
;     ...
;   WAIT_V(0);
;   if (wr == 0) BAR;
;   BAR;
	s_waitcnt vmcnt(0)
	s_movk_i32 s0, 0x100
	v_cmp_gt_u32_e32 vcc, s0, v239
	s_and_saveexec_b64 s[0:1], vcc
	s_cbranch_execz .LBB0_36
	s_barrier

.LBB0_132:
	v_or_b32_e32 v131, 0x10000, v167
	v_add_u32_e32 v136, 0x10400, v167
	v_add_u32_e32 v140, 0x10800, v167
	v_add_u32_e32 v144, 0x10c00, v167
	s_add_i32 s11, s10, 2
	ds_read_b128 v[132:135], v131
	ds_read_b128 v[136:139], v136
	ds_read_b128 v[140:143], v140
	ds_read_b128 v[144:147], v144
	s_cmp_lt_u32 s10, 30
	s_cselect_b32 s12, s8, s5
	s_cselect_b32 s13, s7, s6
	s_cselect_b32 s14, s9, 0
	s_lshl_b32 s13, s13, 11
	s_lshl_b32 s12, s12, 11
	s_or_b32 s15, s14, 64
	s_add_i32 s17, s12, s14
	s_or_b32 s18, s13, 0x40000
	s_add_i32 s16, s13, s14
	s_add_i32 s13, s15, s13
	s_add_i32 s12, s15, s12
	s_lshl_b32 s17, s17, 1
	s_add_i32 s19, s18, s14
	s_add_i32 s18, s18, s15
	s_addk_i32 s9, 0x80
	s_lshl_b32 s16, s16, 1
	s_lshl_b32 s14, s13, 1
	s_lshl_b32 s13, s12, 1
	s_lshl_b32 s15, s19, 1
	s_add_i32 s19, s17, 0x80000
	s_lshl_b32 s12, s18, 1
	s_cmp_gt_u32 s10, 29
	v_add_u32_e32 v148, 0xc000, v0
	v_add_u32_e32 v131, 0xfffc0000, v130
	v_readfirstlane_b32 s10, v148
	s_mov_b32 m0, s10
	ds_read_b128 v[170:173], v166
	ds_read_b128 v[174:177], v166 offset:1024
	ds_read_b128 v[180:183], v166 offset:2048
	ds_read_b128 v[184:187], v166 offset:3072
	ds_read_b128 v[188:191], v166 offset:4096
	ds_read_b128 v[192:195], v166 offset:5120
	ds_read_b128 v[196:199], v166 offset:6144
	ds_read_b128 v[200:203], v166 offset:7168
	global_load_lds_dwordx4 v131, s[86:87]
	v_add_u32_e32 v131, 0xe000, v0
	s_nop 0
	v_readfirstlane_b32 s10, v131
	s_mov_b32 m0, s10
	s_nop 0
	global_load_lds_dwordx4 v130, s[86:87]
	s_waitcnt lgkmcnt(8)
	v_or_b32_e32 v131, 0x14000, v167
	v_add_u32_e32 v148, 0x14400, v167
	ds_read_b128 v[204:207], v131
	ds_read_b128 v[208:211], v148
	v_add_u32_e32 v131, 0x14800, v167
	v_add_u32_e32 v148, 0x14c00, v167
	ds_read_b128 v[212:215], v131
	ds_read_b128 v[216:219], v148
	s_waitcnt vmcnt(8)
	s_waitcnt lgkmcnt(0)
	s_barrier
	v_mfma_f32_16x16x32_bf16 v[98:101], v[132:135], v[170:173], v[98:101]
	v_mfma_f32_16x16x32_bf16 v[102:105], v[140:143], v[170:173], v[102:105]
	v_mfma_f32_16x16x32_bf16 v[126:129], v[132:135], v[180:183], v[126:129]
	v_mfma_f32_16x16x32_bf16 v[122:125], v[140:143], v[180:183], v[122:125]
	v_mfma_f32_16x16x32_bf16 v[118:121], v[132:135], v[188:191], v[118:121]
	v_mfma_f32_16x16x32_bf16 v[114:117], v[140:143], v[188:191], v[114:117]
	v_mfma_f32_16x16x32_bf16 v[110:113], v[132:135], v[196:199], v[110:113]
	v_mfma_f32_16x16x32_bf16 v[106:109], v[140:143], v[196:199], v[106:109]
	v_mfma_f32_16x16x32_bf16 v[98:101], v[136:139], v[174:177], v[98:101]
	v_mfma_f32_16x16x32_bf16 v[102:105], v[144:147], v[174:177], v[102:105]
	v_mfma_f32_16x16x32_bf16 v[126:129], v[136:139], v[184:187], v[126:129]
	v_mfma_f32_16x16x32_bf16 v[122:125], v[144:147], v[184:187], v[122:125]
	v_mfma_f32_16x16x32_bf16 v[118:121], v[136:139], v[192:195], v[118:121]
	v_mfma_f32_16x16x32_bf16 v[114:117], v[144:147], v[192:195], v[114:117]
	v_mfma_f32_16x16x32_bf16 v[110:113], v[136:139], v[200:203], v[110:113]
	v_mfma_f32_16x16x32_bf16 v[106:109], v[144:147], v[200:203], v[106:109]
	v_mfma_f32_16x16x32_bf16 v[66:69], v[204:207], v[170:173], v[66:69]
	v_mfma_f32_16x16x32_bf16 v[70:73], v[212:215], v[170:173], v[70:73]
	v_mfma_f32_16x16x32_bf16 v[74:77], v[204:207], v[180:183], v[74:77]
	v_mfma_f32_16x16x32_bf16 v[78:81], v[212:215], v[180:183], v[78:81]
	v_mfma_f32_16x16x32_bf16 v[82:85], v[204:207], v[188:191], v[82:85]
	v_mfma_f32_16x16x32_bf16 v[86:89], v[212:215], v[188:191], v[86:89]
	v_mfma_f32_16x16x32_bf16 v[90:93], v[204:207], v[196:199], v[90:93]
	v_mfma_f32_16x16x32_bf16 v[94:97], v[212:215], v[196:199], v[94:97]
	v_mfma_f32_16x16x32_bf16 v[66:69], v[208:211], v[174:177], v[66:69]
	v_mfma_f32_16x16x32_bf16 v[70:73], v[216:219], v[174:177], v[70:73]
	v_mfma_f32_16x16x32_bf16 v[74:77], v[208:211], v[184:187], v[74:77]
	v_mfma_f32_16x16x32_bf16 v[78:81], v[216:219], v[184:187], v[78:81]
	v_mfma_f32_16x16x32_bf16 v[82:85], v[208:211], v[192:195], v[82:85]
	v_mfma_f32_16x16x32_bf16 v[86:89], v[216:219], v[192:195], v[86:89]
	v_mfma_f32_16x16x32_bf16 v[90:93], v[208:211], v[200:203], v[90:93]
	v_mfma_f32_16x16x32_bf16 v[94:97], v[216:219], v[200:203], v[94:97]
	s_barrier
	v_readfirstlane_b32 s10, v152
	v_add_u32_e32 v131, s16, v150
	s_mov_b32 m0, s10
	v_readfirstlane_b32 s10, v153
	global_load_lds_dwordx4 v131, s[88:89]
	v_add_u32_e32 v131, s16, v151
	s_mov_b32 m0, s10
	s_nop 0
	global_load_lds_dwordx4 v131, s[88:89]
	v_readfirstlane_b32 s10, v0
	v_add_u32_e32 v131, s17, v150
	s_mov_b32 m0, s10
	v_readfirstlane_b32 s10, v154
	ds_read_b128 v[170:173], v166 offset:16384
	ds_read_b128 v[174:177], v166 offset:17408
	ds_read_b128 v[180:183], v166 offset:18432
	ds_read_b128 v[184:187], v166 offset:19456
	ds_read_b128 v[188:191], v166 offset:20480
	ds_read_b128 v[192:195], v166 offset:21504
	ds_read_b128 v[196:199], v166 offset:22528
	ds_read_b128 v[200:203], v166 offset:23552
	global_load_lds_dwordx4 v131, s[86:87]
	v_add_u32_e32 v131, s17, v151
	s_mov_b32 m0, s10
	s_nop 0
	global_load_lds_dwordx4 v131, s[86:87]
	s_waitcnt vmcnt(6)
	s_waitcnt lgkmcnt(0)
	s_barrier
	v_mfma_f32_16x16x32_bf16 v[34:37], v[132:135], v[170:173], v[34:37]
	v_mfma_f32_16x16x32_bf16 v[38:41], v[140:143], v[170:173], v[38:41]
	v_mfma_f32_16x16x32_bf16 v[42:45], v[132:135], v[180:183], v[42:45]
	v_mfma_f32_16x16x32_bf16 v[46:49], v[140:143], v[180:183], v[46:49]
	v_mfma_f32_16x16x32_bf16 v[50:53], v[132:135], v[188:191], v[50:53]
	v_mfma_f32_16x16x32_bf16 v[54:57], v[140:143], v[188:191], v[54:57]
	v_mfma_f32_16x16x32_bf16 v[58:61], v[132:135], v[196:199], v[58:61]
	v_mfma_f32_16x16x32_bf16 v[62:65], v[140:143], v[196:199], v[62:65]
	v_mfma_f32_16x16x32_bf16 v[34:37], v[136:139], v[174:177], v[34:37]
	v_mfma_f32_16x16x32_bf16 v[38:41], v[144:147], v[174:177], v[38:41]
	v_mfma_f32_16x16x32_bf16 v[42:45], v[136:139], v[184:187], v[42:45]
	v_mfma_f32_16x16x32_bf16 v[46:49], v[144:147], v[184:187], v[46:49]
	v_mfma_f32_16x16x32_bf16 v[50:53], v[136:139], v[192:195], v[50:53]
	v_mfma_f32_16x16x32_bf16 v[54:57], v[144:147], v[192:195], v[54:57]
	v_mfma_f32_16x16x32_bf16 v[58:61], v[136:139], v[200:203], v[58:61]
	v_mfma_f32_16x16x32_bf16 v[62:65], v[144:147], v[200:203], v[62:65]
	v_mfma_f32_16x16x32_bf16 v[2:5], v[204:207], v[170:173], v[2:5]
	v_mfma_f32_16x16x32_bf16 v[6:9], v[212:215], v[170:173], v[6:9]
	v_mfma_f32_16x16x32_bf16 v[10:13], v[204:207], v[180:183], v[10:13]
	v_mfma_f32_16x16x32_bf16 v[14:17], v[212:215], v[180:183], v[14:17]
	v_mfma_f32_16x16x32_bf16 v[18:21], v[204:207], v[188:191], v[18:21]
	v_mfma_f32_16x16x32_bf16 v[22:25], v[212:215], v[188:191], v[22:25]
	v_mfma_f32_16x16x32_bf16 v[26:29], v[204:207], v[196:199], v[26:29]
	v_mfma_f32_16x16x32_bf16 v[30:33], v[212:215], v[196:199], v[30:33]
	v_mfma_f32_16x16x32_bf16 v[2:5], v[208:211], v[174:177], v[2:5]
	v_mfma_f32_16x16x32_bf16 v[6:9], v[216:219], v[174:177], v[6:9]
	v_mfma_f32_16x16x32_bf16 v[10:13], v[208:211], v[184:187], v[10:13]
	v_mfma_f32_16x16x32_bf16 v[14:17], v[216:219], v[184:187], v[14:17]
	v_mfma_f32_16x16x32_bf16 v[18:21], v[208:211], v[192:195], v[18:21]
	v_mfma_f32_16x16x32_bf16 v[22:25], v[216:219], v[192:195], v[22:25]
	v_mfma_f32_16x16x32_bf16 v[26:29], v[208:211], v[200:203], v[26:29]
	v_mfma_f32_16x16x32_bf16 v[30:33], v[216:219], v[200:203], v[30:33]
	s_barrier
	v_readfirstlane_b32 s10, v155
	v_add_u32_e32 v131, s15, v150
	s_mov_b32 m0, s10
	v_readfirstlane_b32 s10, v156
	global_load_lds_dwordx4 v131, s[88:89]
	v_add_u32_e32 v131, s15, v151
	s_mov_b32 m0, s10
	s_nop 0
	global_load_lds_dwordx4 v131, s[88:89]
	v_or_b32_e32 v131, 0x18000, v167
	v_add_u32_e32 v136, 0x18400, v167
	ds_read_b128 v[132:135], v131
	ds_read_b128 v[136:139], v136
	v_add_u32_e32 v131, 0x18800, v167
	v_add_u32_e32 v144, 0x18c00, v167
	ds_read_b128 v[140:143], v131
	ds_read_b128 v[144:147], v144
	v_readfirstlane_b32 s10, v157
	v_add_u32_e32 v131, s19, v150
	s_mov_b32 m0, s10
	v_readfirstlane_b32 s10, v158
	ds_read_b128 v[170:173], v166 offset:32768
	ds_read_b128 v[174:177], v166 offset:33792
	ds_read_b128 v[180:183], v166 offset:34816
	ds_read_b128 v[184:187], v166 offset:35840
	ds_read_b128 v[188:191], v166 offset:36864
	ds_read_b128 v[192:195], v166 offset:37888
	ds_read_b128 v[196:199], v166 offset:38912
	ds_read_b128 v[200:203], v166 offset:39936
	global_load_lds_dwordx4 v131, s[86:87]
	v_add_u32_e32 v131, s19, v151
	s_mov_b32 m0, s10
	s_nop 0
	global_load_lds_dwordx4 v131, s[86:87]
	s_waitcnt lgkmcnt(8)
	v_or_b32_e32 v131, 0x1c000, v167
	v_add_u32_e32 v148, 0x1c400, v167
	ds_read_b128 v[204:207], v131
	ds_read_b128 v[208:211], v148
	v_add_u32_e32 v131, 0x1c800, v167
	v_add_u32_e32 v148, 0x1cc00, v167
	ds_read_b128 v[212:215], v131
	ds_read_b128 v[216:219], v148
	s_waitcnt vmcnt(8)
	s_waitcnt lgkmcnt(0)
	s_barrier
	v_mfma_f32_16x16x32_bf16 v[98:101], v[132:135], v[170:173], v[98:101]
	v_mfma_f32_16x16x32_bf16 v[102:105], v[140:143], v[170:173], v[102:105]
	v_mfma_f32_16x16x32_bf16 v[126:129], v[132:135], v[180:183], v[126:129]
	v_mfma_f32_16x16x32_bf16 v[122:125], v[140:143], v[180:183], v[122:125]
	v_mfma_f32_16x16x32_bf16 v[118:121], v[132:135], v[188:191], v[118:121]
	v_mfma_f32_16x16x32_bf16 v[114:117], v[140:143], v[188:191], v[114:117]
	v_mfma_f32_16x16x32_bf16 v[110:113], v[132:135], v[196:199], v[110:113]
	v_mfma_f32_16x16x32_bf16 v[106:109], v[140:143], v[196:199], v[106:109]
	v_mfma_f32_16x16x32_bf16 v[98:101], v[136:139], v[174:177], v[98:101]
	v_mfma_f32_16x16x32_bf16 v[102:105], v[144:147], v[174:177], v[102:105]
	v_mfma_f32_16x16x32_bf16 v[126:129], v[136:139], v[184:187], v[126:129]
	v_mfma_f32_16x16x32_bf16 v[122:125], v[144:147], v[184:187], v[122:125]
	v_mfma_f32_16x16x32_bf16 v[118:121], v[136:139], v[192:195], v[118:121]
	v_mfma_f32_16x16x32_bf16 v[114:117], v[144:147], v[192:195], v[114:117]
	v_mfma_f32_16x16x32_bf16 v[110:113], v[136:139], v[200:203], v[110:113]
	v_mfma_f32_16x16x32_bf16 v[106:109], v[144:147], v[200:203], v[106:109]
	v_mfma_f32_16x16x32_bf16 v[66:69], v[204:207], v[170:173], v[66:69]
	v_mfma_f32_16x16x32_bf16 v[70:73], v[212:215], v[170:173], v[70:73]
	v_mfma_f32_16x16x32_bf16 v[74:77], v[204:207], v[180:183], v[74:77]
	v_mfma_f32_16x16x32_bf16 v[78:81], v[212:215], v[180:183], v[78:81]
	v_mfma_f32_16x16x32_bf16 v[82:85], v[204:207], v[188:191], v[82:85]
	v_mfma_f32_16x16x32_bf16 v[86:89], v[212:215], v[188:191], v[86:89]
	v_mfma_f32_16x16x32_bf16 v[90:93], v[204:207], v[196:199], v[90:93]
	v_mfma_f32_16x16x32_bf16 v[94:97], v[212:215], v[196:199], v[94:97]
	v_mfma_f32_16x16x32_bf16 v[66:69], v[208:211], v[174:177], v[66:69]
	v_mfma_f32_16x16x32_bf16 v[70:73], v[216:219], v[174:177], v[70:73]
	v_mfma_f32_16x16x32_bf16 v[74:77], v[208:211], v[184:187], v[74:77]
	v_mfma_f32_16x16x32_bf16 v[78:81], v[216:219], v[184:187], v[78:81]
	v_mfma_f32_16x16x32_bf16 v[82:85], v[208:211], v[192:195], v[82:85]
	v_mfma_f32_16x16x32_bf16 v[86:89], v[216:219], v[192:195], v[86:89]
	v_mfma_f32_16x16x32_bf16 v[90:93], v[208:211], v[200:203], v[90:93]
	v_mfma_f32_16x16x32_bf16 v[94:97], v[216:219], v[200:203], v[94:97]
	s_barrier
; DI void gemm_resid(const u16* A, const u16* Bt, int K, const float* xin, float* xout, int bid, int nb, int tid) {
;     ...
;           for (int n = 0; n < 2; ++n) xi[m][n] = *reinterpret_cast<const float4*>(xin + (size_t)ACC_ROW * 2048 + ACC_COL);
	v_readfirstlane_b32 s10, v159
	v_add_u32_e32 v131, s14, v150
	s_mov_b32 m0, s10
	v_readfirstlane_b32 s10, v160
	global_load_lds_dwordx4 v131, s[88:89]
	v_add_u32_e32 v131, s14, v151
	s_mov_b32 m0, s10
	s_nop 0
	global_load_lds_dwordx4 v131, s[88:89]
	v_readfirstlane_b32 s10, v161
	v_add_u32_e32 v131, s13, v150
	s_mov_b32 m0, s10
	v_readfirstlane_b32 s10, v162
	ds_read_b128 v[170:173], v166 offset:49152
	ds_read_b128 v[174:177], v166 offset:50176
	ds_read_b128 v[180:183], v166 offset:51200
	ds_read_b128 v[184:187], v166 offset:52224
	ds_read_b128 v[188:191], v166 offset:53248
	ds_read_b128 v[192:195], v166 offset:54272
	ds_read_b128 v[196:199], v166 offset:55296
	ds_read_b128 v[200:203], v166 offset:56320
	global_load_lds_dwordx4 v131, s[86:87]
	v_add_u32_e32 v131, s13, v151
	s_mov_b32 m0, s10
	s_nop 0
	global_load_lds_dwordx4 v131, s[86:87]
	v_readfirstlane_b32 s10, v163
	v_add_u32_e32 v131, s12, v150
	s_mov_b32 m0, s10
	v_readfirstlane_b32 s10, v165
	global_load_lds_dwordx4 v131, s[88:89]
	v_add_u32_e32 v131, s12, v151
	s_mov_b32 m0, s10
	s_nop 0
	global_load_lds_dwordx4 v131, s[88:89]
	s_waitcnt vmcnt(8)
	s_waitcnt lgkmcnt(0)
	s_barrier
	v_mfma_f32_16x16x32_bf16 v[34:37], v[132:135], v[170:173], v[34:37]
	v_mfma_f32_16x16x32_bf16 v[38:41], v[140:143], v[170:173], v[38:41]
	v_mfma_f32_16x16x32_bf16 v[42:45], v[132:135], v[180:183], v[42:45]
	v_mfma_f32_16x16x32_bf16 v[46:49], v[140:143], v[180:183], v[46:49]
	v_mfma_f32_16x16x32_bf16 v[50:53], v[132:135], v[188:191], v[50:53]
	v_mfma_f32_16x16x32_bf16 v[54:57], v[140:143], v[188:191], v[54:57]
	v_mfma_f32_16x16x32_bf16 v[58:61], v[132:135], v[196:199], v[58:61]
	v_mfma_f32_16x16x32_bf16 v[62:65], v[140:143], v[196:199], v[62:65]
	v_mfma_f32_16x16x32_bf16 v[34:37], v[136:139], v[174:177], v[34:37]
	v_mfma_f32_16x16x32_bf16 v[38:41], v[144:147], v[174:177], v[38:41]
	v_mfma_f32_16x16x32_bf16 v[42:45], v[136:139], v[184:187], v[42:45]
	v_mfma_f32_16x16x32_bf16 v[46:49], v[144:147], v[184:187], v[46:49]
	v_mfma_f32_16x16x32_bf16 v[50:53], v[136:139], v[192:195], v[50:53]
	v_mfma_f32_16x16x32_bf16 v[54:57], v[144:147], v[192:195], v[54:57]
	v_mfma_f32_16x16x32_bf16 v[58:61], v[136:139], v[200:203], v[58:61]
	v_mfma_f32_16x16x32_bf16 v[62:65], v[144:147], v[200:203], v[62:65]
	v_mfma_f32_16x16x32_bf16 v[2:5], v[204:207], v[170:173], v[2:5]
	v_mfma_f32_16x16x32_bf16 v[6:9], v[212:215], v[170:173], v[6:9]
	v_mfma_f32_16x16x32_bf16 v[10:13], v[204:207], v[180:183], v[10:13]
	v_mfma_f32_16x16x32_bf16 v[14:17], v[212:215], v[180:183], v[14:17]
	v_mfma_f32_16x16x32_bf16 v[18:21], v[204:207], v[188:191], v[18:21]
	v_mfma_f32_16x16x32_bf16 v[22:25], v[212:215], v[188:191], v[22:25]
	v_mfma_f32_16x16x32_bf16 v[26:29], v[204:207], v[196:199], v[26:29]
	v_mfma_f32_16x16x32_bf16 v[30:33], v[212:215], v[196:199], v[30:33]
	v_mfma_f32_16x16x32_bf16 v[2:5], v[208:211], v[174:177], v[2:5]
	v_mfma_f32_16x16x32_bf16 v[6:9], v[216:219], v[174:177], v[6:9]
	v_mfma_f32_16x16x32_bf16 v[10:13], v[208:211], v[184:187], v[10:13]
	v_mfma_f32_16x16x32_bf16 v[14:17], v[216:219], v[184:187], v[14:17]
	v_mfma_f32_16x16x32_bf16 v[18:21], v[208:211], v[192:195], v[18:21]
	v_mfma_f32_16x16x32_bf16 v[22:25], v[216:219], v[192:195], v[22:25]
	v_mfma_f32_16x16x32_bf16 v[26:29], v[208:211], v[200:203], v[26:29]
	v_mfma_f32_16x16x32_bf16 v[30:33], v[216:219], v[200:203], v[30:33]
	v_add_u32_e32 v130, 0x100, v130
	s_mov_b32 s10, s11
	s_barrier
	s_cbranch_scc0 .LBB0_132
	v_mov_b32_e32 v131, v239
	s_nop 0
	v_ashrrev_i32_e32 v130, 2, v131
	v_and_b32_e32 v130, 0xffffffc0, v130
	v_and_or_b32 v132, v131, 15, s8
	v_add_u32_e32 v130, v132, v130
	v_lshrrev_b32_e32 v132, 1, v131
	v_lshrrev_b32_e32 v131, 2, v131
	v_and_b32_e32 v132, 0x60, v132
	v_and_b32_e32 v131, 12, v131
	v_or3_b32 v132, v132, v131, s7
	v_ashrrev_i32_e32 v131, 31, v130
	v_ashrrev_i32_e32 v133, 31, v132
	v_lshlrev_b64 v[134:135], 13, v[130:131]
	v_lshl_add_u64 v[136:137], s[48:49], 0, v[134:135]
	v_lshlrev_b64 v[132:133], 2, v[132:133]
	v_lshl_add_u64 v[142:143], v[136:137], 0, v[132:133]
	v_or_b32_e32 v136, 16, v130
	v_ashrrev_i32_e32 v137, 31, v136
	v_lshlrev_b64 v[136:137], 13, v[136:137]
	v_lshl_add_u64 v[138:139], s[48:49], 0, v[136:137]
	v_lshl_add_u64 v[144:145], v[138:139], 0, v[132:133]
	v_or_b32_e32 v138, 32, v130
	v_ashrrev_i32_e32 v139, 31, v138
	v_lshlrev_b64 v[170:171], 13, v[138:139]
	v_lshl_add_u64 v[138:139], s[48:49], 0, v[170:171]
	v_lshl_add_u64 v[146:147], v[138:139], 0, v[132:133]
	v_or_b32_e32 v138, 48, v130
	v_ashrrev_i32_e32 v139, 31, v138
	v_lshlrev_b64 v[172:173], 13, v[138:139]
	v_lshl_add_u64 v[134:135], s[72:73], 0, v[134:135]
	v_lshl_add_u64 v[138:139], s[48:49], 0, v[172:173]
	v_lshl_add_u64 v[140:141], v[134:135], 0, v[132:133]
	v_lshl_add_u64 v[134:135], s[72:73], 0, v[136:137]
	v_lshl_add_u64 v[148:149], v[138:139], 0, v[132:133]
	v_lshl_add_u64 v[138:139], v[134:135], 0, v[132:133]
	v_lshl_add_u64 v[134:135], s[72:73], 0, v[170:171]
	v_lshl_add_u64 v[136:137], v[134:135], 0, v[132:133]
	v_lshl_add_u64 v[134:135], s[72:73], 0, v[172:173]
	v_lshl_add_u64 v[134:135], v[134:135], 0, v[132:133]
	global_load_dwordx4 v[180:183], v[148:149], off offset:64
	global_load_dwordx4 v[184:187], v[148:149], off
	global_load_dwordx4 v[188:191], v[146:147], off offset:64
	global_load_dwordx4 v[192:195], v[146:147], off
	global_load_dwordx4 v[196:199], v[144:145], off offset:64
	global_load_dwordx4 v[200:203], v[144:145], off
	global_load_dwordx4 v[204:207], v[142:143], off offset:64
	global_load_dwordx4 v[208:211], v[142:143], off
	s_waitcnt vmcnt(0)
; DI void gemm_resid(const u16* A, const u16* Bt, int K, const float* xin, float* xout, int bid, int nb, int tid) {
;     ...
;           for (int n = 0; n < 2; ++n) xi[m][n] = *reinterpret_cast<const float4*>(xin + (size_t)ACC_ROW * 2048 + ACC_COL);
; #pragma unroll
;         for (int m = 0; m < 4; ++m)
; #pragma unroll
;           for (int n = 0; n < 2; ++n) {
;             const f32x4 v = acc[ai][bj][m][n];
;             float4 r; r.x = xi[m][n].x + v[0]; r.y = xi[m][n].y + v[1]; r.z = xi[m][n].z + v[2]; r.w = xi[m][n].w + v[3];
;             *reinterpret_cast<float4*>(xout + (size_t)ACC_ROW * 2048 + ACC_COL) = r;
	v_pk_add_f32 v[106:107], v[106:107], v[180:181]
	v_pk_add_f32 v[108:109], v[108:109], v[182:183]
	v_pk_add_f32 v[110:111], v[110:111], v[184:185]
	v_pk_add_f32 v[112:113], v[112:113], v[186:187]
	v_pk_add_f32 v[114:115], v[114:115], v[188:189]
	v_pk_add_f32 v[116:117], v[116:117], v[190:191]
	v_pk_add_f32 v[118:119], v[118:119], v[192:193]
	v_pk_add_f32 v[120:121], v[120:121], v[194:195]
	v_pk_add_f32 v[122:123], v[122:123], v[196:197]
	v_pk_add_f32 v[124:125], v[124:125], v[198:199]
	v_pk_add_f32 v[126:127], v[126:127], v[200:201]
	v_pk_add_f32 v[128:129], v[128:129], v[202:203]
	v_pk_add_f32 v[102:103], v[102:103], v[204:205]
	v_pk_add_f32 v[104:105], v[104:105], v[206:207]
	v_pk_add_f32 v[98:99], v[98:99], v[208:209]
	v_pk_add_f32 v[100:101], v[100:101], v[210:211]
	global_store_dwordx4 v[140:141], v[98:101], off
	global_store_dwordx4 v[140:141], v[102:105], off offset:64
	global_store_dwordx4 v[138:139], v[126:129], off
	global_store_dwordx4 v[138:139], v[122:125], off offset:64
	global_store_dwordx4 v[136:137], v[118:121], off
	global_store_dwordx4 v[136:137], v[114:117], off offset:64
	global_store_dwordx4 v[134:135], v[110:113], off
	global_store_dwordx4 v[134:135], v[106:109], off offset:64
	global_load_dwordx4 v[180:183], v[148:149], off offset:576
	global_load_dwordx4 v[184:187], v[148:149], off offset:512
	global_load_dwordx4 v[188:191], v[146:147], off offset:576
	global_load_dwordx4 v[192:195], v[146:147], off offset:512
	global_load_dwordx4 v[196:199], v[144:145], off offset:576
	global_load_dwordx4 v[200:203], v[144:145], off offset:512
	global_load_dwordx4 v[204:207], v[142:143], off offset:576
	global_load_dwordx4 v[208:211], v[142:143], off offset:512
	s_waitcnt vmcnt(0)
	v_pk_add_f32 v[94:95], v[94:95], v[180:181]
	v_pk_add_f32 v[96:97], v[96:97], v[182:183]
	v_pk_add_f32 v[90:91], v[90:91], v[184:185]
	v_pk_add_f32 v[92:93], v[92:93], v[186:187]
	v_pk_add_f32 v[86:87], v[86:87], v[188:189]
	v_pk_add_f32 v[88:89], v[88:89], v[190:191]
	v_pk_add_f32 v[82:83], v[82:83], v[192:193]
	v_pk_add_f32 v[84:85], v[84:85], v[194:195]
	v_pk_add_f32 v[78:79], v[78:79], v[196:197]
	v_pk_add_f32 v[80:81], v[80:81], v[198:199]
	v_pk_add_f32 v[74:75], v[74:75], v[200:201]
	v_pk_add_f32 v[76:77], v[76:77], v[202:203]
	v_pk_add_f32 v[70:71], v[70:71], v[204:205]
	v_pk_add_f32 v[72:73], v[72:73], v[206:207]
	v_pk_add_f32 v[66:67], v[66:67], v[208:209]
	v_pk_add_f32 v[68:69], v[68:69], v[210:211]
	global_store_dwordx4 v[140:141], v[66:69], off offset:512
	global_store_dwordx4 v[140:141], v[70:73], off offset:576
	global_store_dwordx4 v[138:139], v[74:77], off offset:512
	global_store_dwordx4 v[138:139], v[78:81], off offset:576
	global_store_dwordx4 v[136:137], v[82:85], off offset:512
	global_store_dwordx4 v[136:137], v[86:89], off offset:576
	global_store_dwordx4 v[134:135], v[90:93], off offset:512
	global_store_dwordx4 v[134:135], v[94:97], off offset:576
	v_add_u32_e32 v66, 0x80, v130
	v_ashrrev_i32_e32 v67, 31, v66
	v_lshlrev_b64 v[66:67], 13, v[66:67]
	v_lshl_add_u64 v[68:69], s[48:49], 0, v[66:67]
	v_lshl_add_u64 v[74:75], v[68:69], 0, v[132:133]
	v_add_u32_e32 v68, 0x90, v130
	v_ashrrev_i32_e32 v69, 31, v68
	v_lshlrev_b64 v[68:69], 13, v[68:69]
	v_lshl_add_u64 v[70:71], s[48:49], 0, v[68:69]
	v_lshl_add_u64 v[76:77], v[70:71], 0, v[132:133]
	v_add_u32_e32 v70, 0xa0, v130
	v_ashrrev_i32_e32 v71, 31, v70
	v_lshlrev_b64 v[82:83], 13, v[70:71]
	v_lshl_add_u64 v[70:71], s[48:49], 0, v[82:83]
	v_lshl_add_u64 v[78:79], v[70:71], 0, v[132:133]
	v_add_u32_e32 v70, 0xb0, v130
	v_ashrrev_i32_e32 v71, 31, v70
	v_lshlrev_b64 v[84:85], 13, v[70:71]
	v_lshl_add_u64 v[66:67], s[72:73], 0, v[66:67]
	v_lshl_add_u64 v[70:71], s[48:49], 0, v[84:85]
	v_lshl_add_u64 v[72:73], v[66:67], 0, v[132:133]
	v_lshl_add_u64 v[66:67], s[72:73], 0, v[68:69]
	v_lshl_add_u64 v[80:81], v[70:71], 0, v[132:133]
	v_lshl_add_u64 v[70:71], v[66:67], 0, v[132:133]
	v_lshl_add_u64 v[66:67], s[72:73], 0, v[82:83]
	v_lshl_add_u64 v[68:69], v[66:67], 0, v[132:133]
	v_lshl_add_u64 v[66:67], s[72:73], 0, v[84:85]
	v_lshl_add_u64 v[66:67], v[66:67], 0, v[132:133]
	global_load_dwordx4 v[180:183], v[80:81], off offset:64
	global_load_dwordx4 v[184:187], v[80:81], off
	global_load_dwordx4 v[188:191], v[78:79], off offset:64
	global_load_dwordx4 v[192:195], v[78:79], off
	global_load_dwordx4 v[196:199], v[76:77], off offset:64
	global_load_dwordx4 v[200:203], v[76:77], off
	global_load_dwordx4 v[204:207], v[74:75], off offset:64
	global_load_dwordx4 v[208:211], v[74:75], off
	s_waitcnt vmcnt(0)
; #define WAIT_V(n) asm volatile("s_waitcnt vmcnt(" #n ")" ::: "memory")
; #define BAR __builtin_amdgcn_s_barrier()
; #define EPI_SCHED __builtin_amdgcn_sched_barrier(0)
; template <class EPI>
; DI void gemm_stream(const u16* __restrict__ A, const u16* __restrict__ Bt, const int K, const int nM, const int nN,
;                     const int bid, const int nb, const int tid, EPI epi) {
;     ...
;     brow = brow2; bcol = bcol2; pm = pm2; pn = pn2;
;   }
;   WAIT_V(0);
;   if (wr == 0) BAR;
; DI void gemm_resid(const u16* A, const u16* Bt, int K, const float* xin, float* xout, int bid, int nb, int tid) {
;     ...
;         for (int m = 0; m < 4; ++m)
; #pragma unroll
;           for (int n = 0; n < 2; ++n) {
;             const f32x4 v = acc[ai][bj][m][n];
;             float4 r; r.x = xi[m][n].x + v[0]; r.y = xi[m][n].y + v[1]; r.z = xi[m][n].z + v[2]; r.w = xi[m][n].w + v[3];
;             *reinterpret_cast<float4*>(xout + (size_t)ACC_ROW * 2048 + ACC_COL) = r;
;           }
;         EPI_SCHED;
	v_pk_add_f32 v[62:63], v[62:63], v[180:181]
	v_pk_add_f32 v[64:65], v[64:65], v[182:183]
	v_pk_add_f32 v[58:59], v[58:59], v[184:185]
	v_pk_add_f32 v[60:61], v[60:61], v[186:187]
	v_pk_add_f32 v[54:55], v[54:55], v[188:189]
	v_pk_add_f32 v[56:57], v[56:57], v[190:191]
	v_pk_add_f32 v[50:51], v[50:51], v[192:193]
	v_pk_add_f32 v[52:53], v[52:53], v[194:195]
	v_pk_add_f32 v[46:47], v[46:47], v[196:197]
	v_pk_add_f32 v[48:49], v[48:49], v[198:199]
	v_pk_add_f32 v[42:43], v[42:43], v[200:201]
	v_pk_add_f32 v[44:45], v[44:45], v[202:203]
	v_pk_add_f32 v[38:39], v[38:39], v[204:205]
	v_pk_add_f32 v[40:41], v[40:41], v[206:207]
	v_pk_add_f32 v[34:35], v[34:35], v[208:209]
	v_pk_add_f32 v[36:37], v[36:37], v[210:211]
	global_store_dwordx4 v[72:73], v[34:37], off
	global_store_dwordx4 v[72:73], v[38:41], off offset:64
	global_store_dwordx4 v[70:71], v[42:45], off
	global_store_dwordx4 v[70:71], v[46:49], off offset:64
	global_store_dwordx4 v[68:69], v[50:53], off
	global_store_dwordx4 v[68:69], v[54:57], off offset:64
	global_store_dwordx4 v[66:67], v[58:61], off
	global_store_dwordx4 v[66:67], v[62:65], off offset:64
	global_load_dwordx4 v[180:183], v[80:81], off offset:576
	global_load_dwordx4 v[184:187], v[80:81], off offset:512
	global_load_dwordx4 v[188:191], v[78:79], off offset:576
	global_load_dwordx4 v[192:195], v[78:79], off offset:512
	global_load_dwordx4 v[196:199], v[76:77], off offset:576
	global_load_dwordx4 v[200:203], v[76:77], off offset:512
	global_load_dwordx4 v[204:207], v[74:75], off offset:576
	global_load_dwordx4 v[208:211], v[74:75], off offset:512
	s_waitcnt vmcnt(0)
	v_pk_add_f32 v[30:31], v[30:31], v[180:181]
	v_pk_add_f32 v[32:33], v[32:33], v[182:183]
	v_pk_add_f32 v[26:27], v[26:27], v[184:185]
	v_pk_add_f32 v[28:29], v[28:29], v[186:187]
	v_pk_add_f32 v[22:23], v[22:23], v[188:189]
	v_pk_add_f32 v[24:25], v[24:25], v[190:191]
	v_pk_add_f32 v[18:19], v[18:19], v[192:193]
	v_pk_add_f32 v[20:21], v[20:21], v[194:195]
	v_pk_add_f32 v[14:15], v[14:15], v[196:197]
	v_pk_add_f32 v[16:17], v[16:17], v[198:199]
	v_pk_add_f32 v[10:11], v[10:11], v[200:201]
	v_pk_add_f32 v[12:13], v[12:13], v[202:203]
	v_pk_add_f32 v[6:7], v[6:7], v[204:205]
	v_pk_add_f32 v[8:9], v[8:9], v[206:207]
	v_pk_add_f32 v[2:3], v[2:3], v[208:209]
	v_pk_add_f32 v[4:5], v[4:5], v[210:211]
	global_store_dwordx4 v[72:73], v[2:5], off offset:512
	global_store_dwordx4 v[72:73], v[6:9], off offset:576
	global_store_dwordx4 v[70:71], v[10:13], off offset:512
	global_store_dwordx4 v[70:71], v[14:17], off offset:576
	global_store_dwordx4 v[68:69], v[18:21], off offset:512
	global_store_dwordx4 v[68:69], v[22:25], off offset:576
	global_store_dwordx4 v[66:67], v[26:29], off offset:512
	global_store_dwordx4 v[66:67], v[30:33], off offset:576
	s_and_b64 vcc, exec, s[0:1]
	s_mov_b32 s8, s5
	s_mov_b32 s7, s6
	s_cbranch_vccz .LBB0_129
	s_waitcnt vmcnt(0)
	s_movk_i32 s0, 0x100
	v_cmp_gt_u32_e32 vcc, s0, v239
	s_and_saveexec_b64 s[0:1], vcc
	s_cbranch_execz .LBB0_136
	s_barrier
